# attention row-max: 16-deep dependent v_max3 chain split into two independent interleaved chains (dependent-chain ILP) on v52
# baseline (speedup 1.0000x reference)
.LBB0_210:
	s_or_b64 exec, exec, s[10:11]
	v_max3_f32 v162, v64, s96, v65
	v_max3_f32 v163, v66, s96, v67
	v_max3_f32 v162, v162, v68, v69
	v_max3_f32 v163, v163, v70, v71
	v_max3_f32 v162, v162, v72, v73
	v_max3_f32 v163, v163, v74, v75
	v_max3_f32 v162, v162, v76, v77
	v_max3_f32 v163, v163, v78, v79
	v_max3_f32 v162, v162, v80, v81
	v_max3_f32 v163, v163, v82, v83
	v_max3_f32 v162, v162, v84, v85
	v_max3_f32 v163, v163, v86, v87
	v_max3_f32 v162, v162, v88, v89
	v_max3_f32 v163, v163, v90, v91
	v_max3_f32 v162, v162, v92, v93
	v_max3_f32 v163, v163, v94, v95
	v_max_f32_e32 v162, v162, v163
	v_mov_b32_e32 v163, v162
	s_nop 1
	v_permlane32_swap_b32_e32 v162, v163
	v_max_f32_e32 v162, v162, v163
	v_sub_f32_e32 v163, v162, v170
	v_cmp_lt_f32_e32 vcc, 0x41000000, v163
	s_cbranch_vccnz .Lda_upd0
	v_mov_b32_e32 v234, v170
	v_mov_b32_e32 v170, 1.0
	s_branch .LBB0_212

.LBB0_218:
	s_or_b64 exec, exec, s[8:9]
	v_max3_f32 v162, v96, s96, v97
	v_max3_f32 v163, v98, s96, v99
	v_max3_f32 v162, v162, v100, v101
	v_max3_f32 v163, v163, v102, v103
	v_max3_f32 v162, v162, v104, v105
	v_max3_f32 v163, v163, v106, v107
	v_max3_f32 v162, v162, v108, v109
	v_max3_f32 v163, v163, v110, v111
	v_max3_f32 v162, v162, v112, v113
	v_max3_f32 v163, v163, v114, v115
	v_max3_f32 v162, v162, v116, v117
	v_max3_f32 v163, v163, v118, v119
	v_max3_f32 v162, v162, v120, v121
	v_max3_f32 v163, v163, v122, v123
	v_max3_f32 v162, v162, v124, v125
	v_max3_f32 v163, v163, v126, v127
	v_max_f32_e32 v162, v162, v163
	v_mov_b32_e32 v163, v162
	s_nop 1
	v_permlane32_swap_b32_e32 v162, v163
	v_max_f32_e32 v162, v162, v163
	v_sub_f32_e32 v163, v162, v170
	v_cmp_lt_f32_e32 vcc, 0x41000000, v163
	s_cbranch_vccnz .Lda_upd1
	v_mov_b32_e32 v234, v170
	v_mov_b32_e32 v170, 1.0
	s_branch .LBB0_203
